# nine phase seams inside the row-local chains use a 4-workgroup team barrier (same two 256-row panels, same XCD L2 checked at run time) instead of the grid barrier
# speedup vs baseline: 1.0273x; 1.0235x over previous
.LBB0_423:
	v_readlane_b32 s2, v253, 60
	v_readlane_b32 s3, v253, 61
	s_and_b64 vcc, exec, s[2:3]
	s_cbranch_vccz .LBB0_477
	s_waitcnt vmcnt(0)
	s_waitcnt vmcnt(0)
	s_barrier
	s_mov_b64 s[0:1], exec
	v_readlane_b32 s2, v253, 0
	v_readlane_b32 s3, v253, 1
	s_and_b64 s[2:3], s[0:1], s[2:3]
	s_mov_b64 exec, s[2:3]
	s_cbranch_execz .LBB0_476
	s_cmp_lg_u32 s80, 1
	s_cbranch_scc1 .Ltb_noreg
	v_readlane_b32 s6, v254, 44
	v_readlane_b32 s7, v254, 45
	v_readlane_b32 s12, v254, 40
	s_bfe_u32 s13, s61, 0x60003
	s_sub_u32 s12, s12, s6
	s_add_u32 s12, s12, 0x2000
	s_lshr_b32 s12, s12, 8
	s_lshl_b32 s12, s12, 2
	s_lshl_b32 s12, 1, s12
	s_and_b32 s14, s13, 7
	s_lshr_b32 s13, s13, 3
	s_lshl_b32 s14, s14, 3
	s_add_u32 s13, s13, s14
	s_lshl_b32 s13, s13, 2
	s_add_u32 s13, s13, 0x200
	s_add_u32 s6, s6, s13
	s_addc_u32 s7, s7, 0
	v_mov_b32_e32 v3, s12
	s_nop 0
	global_atomic_add v129, v3, s[6:7]
	s_waitcnt vmcnt(0)
.Ltb_noreg:
	s_mov_b32 s2, 0xf0f80
	s_bitcmp1_b32 s2, s80
	s_cbranch_scc0 .Ltb_grid
	s_bfm_b32 s3, s80, 0
	s_and_b32 s3, s3, s2
	s_bcnt1_i32_b32 s3, s3
	s_add_i32 s3, s3, 1
	s_lshl_b32 s19, s3, 2
	v_readlane_b32 s6, v254, 44
	v_readlane_b32 s7, v254, 45
	s_bfe_u32 s13, s61, 0x60003
	s_and_b32 s14, s13, 7
	s_lshr_b32 s13, s13, 3
	s_lshl_b32 s15, s14, 3
	s_add_u32 s15, s15, s13
	s_lshl_b32 s14, s14, 6
	s_lshl_b32 s13, s13, 2
	s_add_u32 s14, s14, s13
	s_add_u32 s14, s14, 0x300
	s_add_u32 s12, s6, s14
	s_addc_u32 s13, s7, 0
	s_cmp_lg_u32 s80, 7
	s_cbranch_scc1 .Ltb_cached
	s_lshl_b32 s15, s15, 2
	s_add_u32 s15, s15, 0x200
	s_add_u32 s16, s6, s15
	s_addc_u32 s17, s7, 0
	v_readlane_b32 s20, v254, 40
	s_sub_u32 s20, s20, s6
	s_add_u32 s20, s20, 0x2000
	s_lshr_b32 s20, s20, 8
	s_lshl_b32 s20, s20, 2
	s_lshl_b32 s20, 4, s20
	global_load_dword v4, v129, s[16:17] sc1
	s_waitcnt vmcnt(0)
	v_readfirstlane_b32 s21, v4
	s_cmp_eq_u32 s21, s20
	s_cselect_b32 s21, 1, 0
	v_writelane_b32 v255, s21, 45
	s_branch .Ltb_haveflag
.Ltb_cached:
	v_readlane_b32 s21, v255, 45
.Ltb_haveflag:
	s_cmp_eq_u32 s21, 1
	s_cbranch_scc1 .Ltb_nowb
	buffer_wbl2 sc1
	s_waitcnt vmcnt(0)
.Ltb_nowb:
	v_mov_b32_e32 v3, 1
	s_nop 0
	global_atomic_add v129, v3, s[12:13]
	s_mov_b32 s21, 0
.Ltb_spin:
	global_load_dword v4, v129, s[12:13] sc1
	s_waitcnt vmcnt(0)
	v_readfirstlane_b32 s20, v4
	s_cmp_ge_u32 s20, s19
	s_cbranch_scc1 .Ltb_done
	s_add_i32 s21, s21, 1
	s_cmp_lt_u32 s21, 0x2000
	s_cbranch_scc1 .Ltb_spin
.Ltb_done:
	buffer_inv sc1
	s_waitcnt vmcnt(0)
	s_branch .LBB0_476
.Ltb_grid:
	s_waitcnt vmcnt(0) expcnt(0) lgkmcnt(0)
	ds_read_b32 v2, v129
	ds_read_b32 v0, v129 offset:4
	s_waitcnt lgkmcnt(1)
	v_cmp_ne_u32_e32 vcc, 0, v2
	s_cbranch_vccnz .LBB0_440
	s_load_dwordx2 s[2:3], s[38:39], 0x0
	s_load_dword s6, s[38:39], 0x8
	s_mov_b32 s15, 1
	s_waitcnt lgkmcnt(0)
	s_mul_i32 s14, s3, s2
	s_mul_i32 s14, s14, s6
	s_branch .LBB0_428
